# ff1 GEMM epilogue: the 1/sqrt chain reads the preloaded row statistics directly (7 register copies per tile removed)
# speedup vs baseline: 1.0033x; 1.0007x over previous
.LBB0_756:
	v_lshl_add_u32 v164, s4, 8, v168
	v_ashrrev_i32_e32 v165, 31, v164
	v_lshl_add_u64 v[160:161], v[164:165], 2, s[12:13]
	global_load_dword v177, v[160:161], off
	global_load_dword v230, v[160:161], off offset:64
	global_load_dword v231, v[160:161], off offset:128
	global_load_dword v232, v[160:161], off offset:192
	global_load_dword v233, v[160:161], off offset:512
	global_load_dword v234, v[160:161], off offset:576
	global_load_dword v235, v[160:161], off offset:640
	global_load_dword v236, v[160:161], off offset:704
	s_ashr_i32 s4, s4, 4
	s_ashr_i32 s5, s4, 31
	s_lshl_b64 s[4:5], s[4:5], 14
	v_lshl_or_b32 v162, s3, 8, v170
	s_add_u32 s4, s67, s4
	v_ashrrev_i32_e32 v163, 31, v162
	s_addc_u32 s5, s68, s5
	v_lshl_add_u64 v[88:89], v[162:163], 2, s[4:5]
	global_load_dwordx4 v[100:103], v[88:89], off
	global_load_dwordx4 v[96:99], v[88:89], off offset:16
	global_load_dwordx4 v[92:95], v[88:89], off offset:512
	s_nop 0
	global_load_dwordx4 v[88:91], v[88:89], off offset:528
	v_lshlrev_b64 v[166:167], 1, v[162:163]
	v_lshlrev_b64 v[178:179], 13, v[164:165]
	v_or_b32_e32 v176, 16, v164
	s_waitcnt vmcnt(11)
	v_fmamk_f32 v162, v177, 0x3a800000, v174
	v_mul_f32_e32 v163, 0x4f800000, v162
	v_cmp_gt_f32_e32 vcc, s75, v162
	v_ashrrev_i32_e32 v177, 31, v176
	s_nop 0
	v_cndmask_b32_e32 v165, v162, v163, vcc
	v_sqrt_f32_e32 v180, v165
	v_lshl_add_u64 v[162:163], s[22:23], 0, v[178:179]
	v_lshl_add_u64 v[162:163], v[162:163], 0, v[166:167]
	v_lshl_add_u64 v[178:179], v[176:177], 2, s[12:13]
	v_add_u32_e32 v181, -1, v180
	v_add_u32_e32 v182, 1, v180
	v_fma_f32 v183, -v181, v180, v165
	v_fma_f32 v184, -v182, v180, v165
	v_cmp_ge_f32_e64 s[4:5], 0, v183
	s_nop 1
	v_cndmask_b32_e64 v180, v180, v181, s[4:5]
	v_cmp_lt_f32_e64 s[4:5], 0, v184
	s_nop 1
	v_cndmask_b32_e64 v180, v180, v182, s[4:5]
	v_mul_f32_e32 v181, 0x37800000, v180
	v_cndmask_b32_e32 v180, v180, v181, vcc
	v_cmp_class_f32_e32 vcc, v165, v175
	s_nop 1
	v_cndmask_b32_e32 v165, v180, v165, vcc
	v_div_scale_f32 v180, s[4:5], v165, v165, 1.0
	v_rcp_f32_e32 v181, v180
	v_div_scale_f32 v182, vcc, 1.0, v165, 1.0
	v_fma_f32 v183, -v180, v181, 1.0
	v_fmac_f32_e32 v181, v183, v181
	v_mul_f32_e32 v183, v182, v181
	v_fma_f32 v184, -v180, v183, v182
	v_fmac_f32_e32 v183, v184, v181
	v_fma_f32 v180, -v180, v183, v182
	v_div_fmas_f32 v180, v180, v181, v183
	v_div_fixup_f32 v180, v180, v165, 1.0
	s_waitcnt vmcnt(0)
	v_pk_fma_f32 v[142:143], v[142:143], v[180:181], v[102:103] op_sel_hi:[1,0,1]
	v_pk_fma_f32 v[140:141], v[140:141], v[180:181], v[100:101] op_sel_hi:[1,0,1]
	v_pk_fma_f32 v[138:139], v[138:139], v[180:181], v[98:99] op_sel_hi:[1,0,1]
	v_pk_fma_f32 v[136:137], v[136:137], v[180:181], v[96:97] op_sel_hi:[1,0,1]
	v_pk_fma_f32 v[134:135], v[134:135], v[180:181], v[94:95] op_sel_hi:[1,0,1]
	v_pk_fma_f32 v[132:133], v[132:133], v[180:181], v[92:93] op_sel_hi:[1,0,1]
	v_pk_fma_f32 v[130:131], v[130:131], v[180:181], v[90:91] op_sel_hi:[1,0,1]
	v_pk_fma_f32 v[128:129], v[128:129], v[180:181], v[88:89] op_sel_hi:[1,0,1]
	v_max_f32_e32 v140, 0, v140
	v_max_f32_e32 v136, 0, v136
	v_max_f32_e32 v141, 0, v141
	v_max_f32_e32 v137, 0, v137
	v_max_f32_e32 v142, 0, v142
	v_max_f32_e32 v138, 0, v138
	v_max_f32_e32 v143, 0, v143
	v_max_f32_e32 v139, 0, v139
	v_max_f32_e32 v132, 0, v132
	v_max_f32_e32 v128, 0, v128
	v_max_f32_e32 v133, 0, v133
	v_max_f32_e32 v129, 0, v129
	v_max_f32_e32 v134, 0, v134
	v_max_f32_e32 v130, 0, v130
	v_max_f32_e32 v135, 0, v135
	v_max_f32_e32 v131, 0, v131
	v_pk_mul_f32 v[140:141], v[140:141], v[140:141]
	v_pk_mul_f32 v[136:137], v[136:137], v[136:137]
	v_pk_mul_f32 v[142:143], v[142:143], v[142:143]
	v_pk_mul_f32 v[138:139], v[138:139], v[138:139]
	v_pk_mul_f32 v[132:133], v[132:133], v[132:133]
	v_pk_mul_f32 v[180:181], v[128:129], v[128:129]
	v_pk_mul_f32 v[134:135], v[134:135], v[134:135]
	v_pk_mul_f32 v[182:183], v[130:131], v[130:131]
	v_cvt_pk_bf16_f32 v128, v140, v141
	v_cvt_pk_bf16_f32 v129, v142, v143
	v_cvt_pk_bf16_f32 v130, v136, v137
	v_cvt_pk_bf16_f32 v131, v138, v139
	v_cvt_pk_bf16_f32 v132, v132, v133
	v_cvt_pk_bf16_f32 v133, v134, v135
	v_cvt_pk_bf16_f32 v134, v180, v181
	v_cvt_pk_bf16_f32 v135, v182, v183
	global_store_dwordx4 v[162:163], v[128:131], off
	global_store_dwordx4 v[162:163], v[132:135], off offset:256
	s_nop 1
	v_or_b32_e32 v128, 32, v164
	v_ashrrev_i32_e32 v129, 31, v128
	v_lshl_add_u64 v[132:133], v[128:129], 2, s[12:13]
	s_nop 0
	v_fmamk_f32 v130, v230, 0x3a800000, v174
	v_mul_f32_e32 v131, 0x4f800000, v130
	v_cmp_gt_f32_e32 vcc, s75, v130
	s_nop 1
	v_cndmask_b32_e32 v134, v130, v131, vcc
	v_sqrt_f32_e32 v135, v134
	v_lshlrev_b64 v[130:131], 13, v[176:177]
	v_lshl_add_u64 v[130:131], s[22:23], 0, v[130:131]
	v_lshl_add_u64 v[130:131], v[130:131], 0, v[166:167]
	v_add_u32_e32 v136, -1, v135
	v_add_u32_e32 v137, 1, v135
	v_fma_f32 v138, -v136, v135, v134
	v_fma_f32 v139, -v137, v135, v134
	v_cmp_ge_f32_e64 s[4:5], 0, v138
	s_nop 1
	v_cndmask_b32_e64 v135, v135, v136, s[4:5]
	v_cmp_lt_f32_e64 s[4:5], 0, v139
	s_nop 1
	v_cndmask_b32_e64 v135, v135, v137, s[4:5]
	v_mul_f32_e32 v136, 0x37800000, v135
	v_cndmask_b32_e32 v135, v135, v136, vcc
	v_cmp_class_f32_e32 vcc, v134, v175
	s_nop 1
	v_cndmask_b32_e32 v134, v135, v134, vcc
	v_div_scale_f32 v135, s[4:5], v134, v134, 1.0
	v_rcp_f32_e32 v136, v135
	v_div_scale_f32 v137, vcc, 1.0, v134, 1.0
	v_fma_f32 v138, -v135, v136, 1.0
	v_fmac_f32_e32 v136, v138, v136
	v_mul_f32_e32 v138, v137, v136
	v_fma_f32 v139, -v135, v138, v137
	v_fmac_f32_e32 v138, v139, v136
	v_fma_f32 v135, -v135, v138, v137
	v_div_fmas_f32 v135, v135, v136, v138
	v_div_fixup_f32 v134, v135, v134, 1.0
	v_pk_fma_f32 v[126:127], v[126:127], v[134:135], v[102:103] op_sel_hi:[1,0,1]
	v_pk_fma_f32 v[124:125], v[124:125], v[134:135], v[100:101] op_sel_hi:[1,0,1]
	v_pk_fma_f32 v[122:123], v[122:123], v[134:135], v[98:99] op_sel_hi:[1,0,1]
	v_pk_fma_f32 v[120:121], v[120:121], v[134:135], v[96:97] op_sel_hi:[1,0,1]
	v_pk_fma_f32 v[118:119], v[118:119], v[134:135], v[94:95] op_sel_hi:[1,0,1]
	v_pk_fma_f32 v[116:117], v[116:117], v[134:135], v[92:93] op_sel_hi:[1,0,1]
	v_pk_fma_f32 v[114:115], v[114:115], v[134:135], v[90:91] op_sel_hi:[1,0,1]
	v_pk_fma_f32 v[112:113], v[112:113], v[134:135], v[88:89] op_sel_hi:[1,0,1]
	v_max_f32_e32 v124, 0, v124
	v_max_f32_e32 v120, 0, v120
	v_max_f32_e32 v125, 0, v125
	v_max_f32_e32 v121, 0, v121
	v_max_f32_e32 v126, 0, v126
	v_max_f32_e32 v122, 0, v122
	v_max_f32_e32 v127, 0, v127
	v_max_f32_e32 v123, 0, v123
	v_max_f32_e32 v116, 0, v116
	v_max_f32_e32 v112, 0, v112
	v_max_f32_e32 v117, 0, v117
	v_max_f32_e32 v113, 0, v113
	v_max_f32_e32 v118, 0, v118
	v_max_f32_e32 v114, 0, v114
	v_max_f32_e32 v119, 0, v119
	v_max_f32_e32 v115, 0, v115
	v_pk_mul_f32 v[124:125], v[124:125], v[124:125]
	v_pk_mul_f32 v[120:121], v[120:121], v[120:121]
	v_pk_mul_f32 v[126:127], v[126:127], v[126:127]
	v_pk_mul_f32 v[122:123], v[122:123], v[122:123]
	v_pk_mul_f32 v[116:117], v[116:117], v[116:117]
	v_pk_mul_f32 v[134:135], v[112:113], v[112:113]
	v_pk_mul_f32 v[118:119], v[118:119], v[118:119]
	v_pk_mul_f32 v[136:137], v[114:115], v[114:115]
	v_cvt_pk_bf16_f32 v112, v124, v125
	v_cvt_pk_bf16_f32 v113, v126, v127
	v_cvt_pk_bf16_f32 v114, v120, v121
	v_cvt_pk_bf16_f32 v115, v122, v123
	v_cvt_pk_bf16_f32 v116, v116, v117
	v_cvt_pk_bf16_f32 v117, v118, v119
	v_cvt_pk_bf16_f32 v118, v134, v135
	v_cvt_pk_bf16_f32 v119, v136, v137
	global_store_dwordx4 v[130:131], v[112:115], off
	global_store_dwordx4 v[130:131], v[116:119], off offset:256
	s_nop 1
	v_or_b32_e32 v112, 48, v164
	v_ashrrev_i32_e32 v113, 31, v112
	v_lshl_add_u64 v[116:117], v[112:113], 2, s[12:13]
	s_nop 0
	v_fmamk_f32 v114, v231, 0x3a800000, v174
	v_mul_f32_e32 v115, 0x4f800000, v114
	v_cmp_gt_f32_e32 vcc, s75, v114
	s_nop 1
	v_cndmask_b32_e32 v118, v114, v115, vcc
	v_sqrt_f32_e32 v119, v118
	v_lshlrev_b64 v[114:115], 13, v[128:129]
	v_lshl_add_u64 v[114:115], s[22:23], 0, v[114:115]
	v_lshl_add_u64 v[114:115], v[114:115], 0, v[166:167]
	v_add_u32_e32 v120, -1, v119
	v_add_u32_e32 v121, 1, v119
	v_fma_f32 v122, -v120, v119, v118
	v_fma_f32 v123, -v121, v119, v118
	v_cmp_ge_f32_e64 s[4:5], 0, v122
	s_nop 1
	v_cndmask_b32_e64 v119, v119, v120, s[4:5]
	v_cmp_lt_f32_e64 s[4:5], 0, v123
	s_nop 1
	v_cndmask_b32_e64 v119, v119, v121, s[4:5]
	v_mul_f32_e32 v120, 0x37800000, v119
	v_cndmask_b32_e32 v119, v119, v120, vcc
	v_cmp_class_f32_e32 vcc, v118, v175
	s_nop 1
	v_cndmask_b32_e32 v118, v119, v118, vcc
	v_div_scale_f32 v119, s[4:5], v118, v118, 1.0
	v_rcp_f32_e32 v120, v119
	v_div_scale_f32 v121, vcc, 1.0, v118, 1.0
	v_fma_f32 v122, -v119, v120, 1.0
	v_fmac_f32_e32 v120, v122, v120
	v_mul_f32_e32 v122, v121, v120
	v_fma_f32 v123, -v119, v122, v121
	v_fmac_f32_e32 v122, v123, v120
	v_fma_f32 v119, -v119, v122, v121
	v_div_fmas_f32 v119, v119, v120, v122
	v_div_fixup_f32 v118, v119, v118, 1.0
	v_pk_fma_f32 v[110:111], v[110:111], v[118:119], v[102:103] op_sel_hi:[1,0,1]
	v_pk_fma_f32 v[108:109], v[108:109], v[118:119], v[100:101] op_sel_hi:[1,0,1]
	v_pk_fma_f32 v[106:107], v[106:107], v[118:119], v[98:99] op_sel_hi:[1,0,1]
	v_pk_fma_f32 v[104:105], v[104:105], v[118:119], v[96:97] op_sel_hi:[1,0,1]
	v_pk_fma_f32 v[86:87], v[86:87], v[118:119], v[94:95] op_sel_hi:[1,0,1]
	v_pk_fma_f32 v[84:85], v[84:85], v[118:119], v[92:93] op_sel_hi:[1,0,1]
	v_pk_fma_f32 v[82:83], v[82:83], v[118:119], v[90:91] op_sel_hi:[1,0,1]
	v_pk_fma_f32 v[80:81], v[80:81], v[118:119], v[88:89] op_sel_hi:[1,0,1]
	v_max_f32_e32 v108, 0, v108
	v_max_f32_e32 v104, 0, v104
	v_max_f32_e32 v109, 0, v109
	v_max_f32_e32 v105, 0, v105
	v_max_f32_e32 v110, 0, v110
	v_max_f32_e32 v106, 0, v106
	v_max_f32_e32 v111, 0, v111
	v_max_f32_e32 v107, 0, v107
	v_max_f32_e32 v84, 0, v84
	v_max_f32_e32 v80, 0, v80
	v_max_f32_e32 v85, 0, v85
	v_max_f32_e32 v81, 0, v81
	v_max_f32_e32 v86, 0, v86
	v_max_f32_e32 v82, 0, v82
	v_max_f32_e32 v87, 0, v87
	v_max_f32_e32 v83, 0, v83
	v_pk_mul_f32 v[108:109], v[108:109], v[108:109]
	v_pk_mul_f32 v[104:105], v[104:105], v[104:105]
	v_pk_mul_f32 v[110:111], v[110:111], v[110:111]
	v_pk_mul_f32 v[106:107], v[106:107], v[106:107]
	v_pk_mul_f32 v[84:85], v[84:85], v[84:85]
	v_pk_mul_f32 v[118:119], v[80:81], v[80:81]
	v_pk_mul_f32 v[86:87], v[86:87], v[86:87]
	v_pk_mul_f32 v[120:121], v[82:83], v[82:83]
	v_cvt_pk_bf16_f32 v80, v108, v109
	v_cvt_pk_bf16_f32 v81, v110, v111
	v_cvt_pk_bf16_f32 v82, v104, v105
	v_cvt_pk_bf16_f32 v83, v106, v107
	v_cvt_pk_bf16_f32 v84, v84, v85
	v_cvt_pk_bf16_f32 v85, v86, v87
	v_cvt_pk_bf16_f32 v86, v118, v119
	v_cvt_pk_bf16_f32 v87, v120, v121
	global_store_dwordx4 v[114:115], v[80:83], off
	global_store_dwordx4 v[114:115], v[84:87], off offset:256
	s_nop 1
	s_nop 0
	v_fmamk_f32 v80, v232, 0x3a800000, v174
	v_mul_f32_e32 v81, 0x4f800000, v80
	v_cmp_gt_f32_e32 vcc, s75, v80
	s_nop 1
	v_cndmask_b32_e32 v82, v80, v81, vcc
	v_sqrt_f32_e32 v83, v82
	v_lshlrev_b64 v[80:81], 13, v[112:113]
	v_lshl_add_u64 v[80:81], s[22:23], 0, v[80:81]
	v_lshl_add_u64 v[80:81], v[80:81], 0, v[166:167]
	v_add_u32_e32 v84, -1, v83
	v_add_u32_e32 v85, 1, v83
	v_fma_f32 v86, -v84, v83, v82
	v_fma_f32 v87, -v85, v83, v82
	v_cmp_ge_f32_e64 s[4:5], 0, v86
	s_nop 1
	v_cndmask_b32_e64 v83, v83, v84, s[4:5]
	v_cmp_lt_f32_e64 s[4:5], 0, v87
	s_nop 1
	v_cndmask_b32_e64 v83, v83, v85, s[4:5]
	v_mul_f32_e32 v84, 0x37800000, v83
	v_cndmask_b32_e32 v83, v83, v84, vcc
	v_cmp_class_f32_e32 vcc, v82, v175
	s_nop 1
	v_cndmask_b32_e32 v82, v83, v82, vcc
	v_div_scale_f32 v83, s[4:5], v82, v82, 1.0
	v_rcp_f32_e32 v84, v83
	v_div_scale_f32 v85, vcc, 1.0, v82, 1.0
	v_fma_f32 v86, -v83, v84, 1.0
	v_fmac_f32_e32 v84, v86, v84
	v_mul_f32_e32 v86, v85, v84
	v_fma_f32 v87, -v83, v86, v85
	v_fmac_f32_e32 v86, v87, v84
	v_fma_f32 v83, -v83, v86, v85
	v_div_fmas_f32 v83, v83, v84, v86
	v_div_fixup_f32 v82, v83, v82, 1.0
	v_pk_fma_f32 v[78:79], v[78:79], v[82:83], v[102:103] op_sel_hi:[1,0,1]
	v_pk_fma_f32 v[76:77], v[76:77], v[82:83], v[100:101] op_sel_hi:[1,0,1]
	v_pk_fma_f32 v[74:75], v[74:75], v[82:83], v[98:99] op_sel_hi:[1,0,1]
	v_pk_fma_f32 v[72:73], v[72:73], v[82:83], v[96:97] op_sel_hi:[1,0,1]
	v_pk_fma_f32 v[70:71], v[70:71], v[82:83], v[94:95] op_sel_hi:[1,0,1]
	v_pk_fma_f32 v[68:69], v[68:69], v[82:83], v[92:93] op_sel_hi:[1,0,1]
	v_pk_fma_f32 v[66:67], v[66:67], v[82:83], v[90:91] op_sel_hi:[1,0,1]
	v_pk_fma_f32 v[64:65], v[64:65], v[82:83], v[88:89] op_sel_hi:[1,0,1]
	v_max_f32_e32 v76, 0, v76
	v_max_f32_e32 v72, 0, v72
	v_max_f32_e32 v77, 0, v77
	v_max_f32_e32 v73, 0, v73
	v_max_f32_e32 v78, 0, v78
	v_max_f32_e32 v74, 0, v74
	v_max_f32_e32 v79, 0, v79
	v_max_f32_e32 v75, 0, v75
	v_max_f32_e32 v68, 0, v68
	v_max_f32_e32 v64, 0, v64
	v_max_f32_e32 v69, 0, v69
	v_max_f32_e32 v65, 0, v65
	v_max_f32_e32 v70, 0, v70
	v_max_f32_e32 v66, 0, v66
	v_max_f32_e32 v71, 0, v71
	v_max_f32_e32 v67, 0, v67
	v_pk_mul_f32 v[76:77], v[76:77], v[76:77]
	v_pk_mul_f32 v[72:73], v[72:73], v[72:73]
	v_pk_mul_f32 v[78:79], v[78:79], v[78:79]
	v_pk_mul_f32 v[74:75], v[74:75], v[74:75]
	v_pk_mul_f32 v[68:69], v[68:69], v[68:69]
	v_pk_mul_f32 v[82:83], v[64:65], v[64:65]
	v_pk_mul_f32 v[70:71], v[70:71], v[70:71]
	v_pk_mul_f32 v[84:85], v[66:67], v[66:67]
	v_cvt_pk_bf16_f32 v64, v76, v77
	v_cvt_pk_bf16_f32 v65, v78, v79
	v_cvt_pk_bf16_f32 v66, v72, v73
	v_cvt_pk_bf16_f32 v67, v74, v75
	v_cvt_pk_bf16_f32 v68, v68, v69
	v_cvt_pk_bf16_f32 v69, v70, v71
	v_cvt_pk_bf16_f32 v70, v82, v83
	v_cvt_pk_bf16_f32 v71, v84, v85
	global_store_dwordx4 v[80:81], v[64:67], off
	global_store_dwordx4 v[80:81], v[68:71], off offset:256
	s_nop 1
	s_nop 0
	v_fmamk_f32 v64, v233, 0x3a800000, v174
	v_mul_f32_e32 v65, 0x4f800000, v64
	v_cmp_gt_f32_e32 vcc, s75, v64
	s_nop 1
	v_cndmask_b32_e32 v66, v64, v65, vcc
	v_sqrt_f32_e32 v67, v66
	v_lshl_add_u64 v[64:65], v[162:163], 0, s[20:21]
	v_add_u32_e32 v68, -1, v67
	v_add_u32_e32 v69, 1, v67
	v_fma_f32 v70, -v68, v67, v66
	v_fma_f32 v71, -v69, v67, v66
	v_cmp_ge_f32_e64 s[4:5], 0, v70
	s_nop 1
	v_cndmask_b32_e64 v67, v67, v68, s[4:5]
	v_cmp_lt_f32_e64 s[4:5], 0, v71
	s_nop 1
	v_cndmask_b32_e64 v67, v67, v69, s[4:5]
	v_mul_f32_e32 v68, 0x37800000, v67
	v_cndmask_b32_e32 v67, v67, v68, vcc
	v_cmp_class_f32_e32 vcc, v66, v175
	s_nop 1
	v_cndmask_b32_e32 v68, v67, v66, vcc
	v_div_scale_f32 v69, s[4:5], v68, v68, 1.0
	v_rcp_f32_e32 v70, v69
	v_add_co_u32_e32 v66, vcc, s76, v162
	v_fma_f32 v72, -v69, v70, 1.0
	s_nop 0
	v_addc_co_u32_e32 v67, vcc, 0, v163, vcc
	v_div_scale_f32 v71, vcc, 1.0, v68, 1.0
	v_fmac_f32_e32 v70, v72, v70
	v_mul_f32_e32 v72, v71, v70
	v_fma_f32 v73, -v69, v72, v71
	v_fmac_f32_e32 v72, v73, v70
	v_fma_f32 v69, -v69, v72, v71
	v_div_fmas_f32 v69, v69, v70, v72
	v_div_fixup_f32 v68, v69, v68, 1.0
	v_pk_fma_f32 v[62:63], v[62:63], v[68:69], v[102:103] op_sel_hi:[1,0,1]
	v_pk_fma_f32 v[60:61], v[60:61], v[68:69], v[100:101] op_sel_hi:[1,0,1]
	v_pk_fma_f32 v[58:59], v[58:59], v[68:69], v[98:99] op_sel_hi:[1,0,1]
	v_pk_fma_f32 v[56:57], v[56:57], v[68:69], v[96:97] op_sel_hi:[1,0,1]
	v_pk_fma_f32 v[54:55], v[54:55], v[68:69], v[94:95] op_sel_hi:[1,0,1]
	v_pk_fma_f32 v[52:53], v[52:53], v[68:69], v[92:93] op_sel_hi:[1,0,1]
	v_pk_fma_f32 v[50:51], v[50:51], v[68:69], v[90:91] op_sel_hi:[1,0,1]
	v_pk_fma_f32 v[48:49], v[48:49], v[68:69], v[88:89] op_sel_hi:[1,0,1]
	v_max_f32_e32 v60, 0, v60
	v_max_f32_e32 v56, 0, v56
	v_max_f32_e32 v61, 0, v61
	v_max_f32_e32 v57, 0, v57
	v_max_f32_e32 v62, 0, v62
	v_max_f32_e32 v58, 0, v58
	v_max_f32_e32 v63, 0, v63
	v_max_f32_e32 v59, 0, v59
	v_max_f32_e32 v52, 0, v52
	v_max_f32_e32 v48, 0, v48
	v_max_f32_e32 v53, 0, v53
	v_max_f32_e32 v49, 0, v49
	v_max_f32_e32 v54, 0, v54
	v_max_f32_e32 v50, 0, v50
	v_max_f32_e32 v55, 0, v55
	v_max_f32_e32 v51, 0, v51
	v_pk_mul_f32 v[60:61], v[60:61], v[60:61]
	v_pk_mul_f32 v[56:57], v[56:57], v[56:57]
	v_pk_mul_f32 v[62:63], v[62:63], v[62:63]
	v_pk_mul_f32 v[58:59], v[58:59], v[58:59]
	v_pk_mul_f32 v[52:53], v[52:53], v[52:53]
	v_pk_mul_f32 v[68:69], v[48:49], v[48:49]
	v_pk_mul_f32 v[54:55], v[54:55], v[54:55]
	v_pk_mul_f32 v[70:71], v[50:51], v[50:51]
	v_cvt_pk_bf16_f32 v48, v60, v61
	v_cvt_pk_bf16_f32 v49, v62, v63
	v_cvt_pk_bf16_f32 v50, v56, v57
	v_cvt_pk_bf16_f32 v51, v58, v59
	v_cvt_pk_bf16_f32 v52, v52, v53
	v_cvt_pk_bf16_f32 v53, v54, v55
	v_cvt_pk_bf16_f32 v54, v68, v69
	v_cvt_pk_bf16_f32 v55, v70, v71
	global_store_dwordx4 v[66:67], v[48:51], off
	global_store_dwordx4 v[64:65], v[52:55], off offset:256
	s_nop 1
	s_nop 0
	v_fmamk_f32 v48, v234, 0x3a800000, v174
	v_mul_f32_e32 v49, 0x4f800000, v48
	v_cmp_gt_f32_e32 vcc, s75, v48
	s_nop 1
	v_cndmask_b32_e32 v50, v48, v49, vcc
	v_sqrt_f32_e32 v51, v50
	v_lshl_add_u64 v[48:49], v[162:163], 0, s[24:25]
	v_add_u32_e32 v52, -1, v51
	v_add_u32_e32 v53, 1, v51
	v_fma_f32 v54, -v52, v51, v50
	v_fma_f32 v55, -v53, v51, v50
	v_cmp_ge_f32_e64 s[4:5], 0, v54
	s_nop 1
	v_cndmask_b32_e64 v51, v51, v52, s[4:5]
	v_cmp_lt_f32_e64 s[4:5], 0, v55
	s_nop 1
	v_cndmask_b32_e64 v51, v51, v53, s[4:5]
	v_mul_f32_e32 v52, 0x37800000, v51
	v_cndmask_b32_e32 v51, v51, v52, vcc
	v_cmp_class_f32_e32 vcc, v50, v175
	s_nop 1
	v_cndmask_b32_e32 v52, v51, v50, vcc
	v_div_scale_f32 v53, s[4:5], v52, v52, 1.0
	v_rcp_f32_e32 v54, v53
	v_add_co_u32_e32 v50, vcc, s77, v162
	v_fma_f32 v56, -v53, v54, 1.0
	s_nop 0
	v_addc_co_u32_e32 v51, vcc, 0, v163, vcc
	v_div_scale_f32 v55, vcc, 1.0, v52, 1.0
	v_fmac_f32_e32 v54, v56, v54
	v_mul_f32_e32 v56, v55, v54
	v_fma_f32 v57, -v53, v56, v55
	v_fmac_f32_e32 v56, v57, v54
	v_fma_f32 v53, -v53, v56, v55
	v_div_fmas_f32 v53, v53, v54, v56
	v_div_fixup_f32 v52, v53, v52, 1.0
	v_pk_fma_f32 v[46:47], v[46:47], v[52:53], v[102:103] op_sel_hi:[1,0,1]
	v_pk_fma_f32 v[44:45], v[44:45], v[52:53], v[100:101] op_sel_hi:[1,0,1]
	v_pk_fma_f32 v[42:43], v[42:43], v[52:53], v[98:99] op_sel_hi:[1,0,1]
	v_pk_fma_f32 v[40:41], v[40:41], v[52:53], v[96:97] op_sel_hi:[1,0,1]
	v_pk_fma_f32 v[38:39], v[38:39], v[52:53], v[94:95] op_sel_hi:[1,0,1]
	v_pk_fma_f32 v[36:37], v[36:37], v[52:53], v[92:93] op_sel_hi:[1,0,1]
	v_pk_fma_f32 v[34:35], v[34:35], v[52:53], v[90:91] op_sel_hi:[1,0,1]
	v_pk_fma_f32 v[32:33], v[32:33], v[52:53], v[88:89] op_sel_hi:[1,0,1]
	v_max_f32_e32 v44, 0, v44
	v_max_f32_e32 v40, 0, v40
	v_max_f32_e32 v45, 0, v45
	v_max_f32_e32 v41, 0, v41
	v_max_f32_e32 v46, 0, v46
	v_max_f32_e32 v42, 0, v42
	v_max_f32_e32 v47, 0, v47
	v_max_f32_e32 v43, 0, v43
	v_max_f32_e32 v36, 0, v36
	v_max_f32_e32 v32, 0, v32
	v_max_f32_e32 v37, 0, v37
	v_max_f32_e32 v33, 0, v33
	v_max_f32_e32 v38, 0, v38
	v_max_f32_e32 v34, 0, v34
	v_max_f32_e32 v39, 0, v39
	v_max_f32_e32 v35, 0, v35
	v_pk_mul_f32 v[44:45], v[44:45], v[44:45]
	v_pk_mul_f32 v[40:41], v[40:41], v[40:41]
	v_pk_mul_f32 v[46:47], v[46:47], v[46:47]
	v_pk_mul_f32 v[42:43], v[42:43], v[42:43]
	v_pk_mul_f32 v[36:37], v[36:37], v[36:37]
	v_pk_mul_f32 v[52:53], v[32:33], v[32:33]
	v_pk_mul_f32 v[38:39], v[38:39], v[38:39]
	v_pk_mul_f32 v[54:55], v[34:35], v[34:35]
	v_cvt_pk_bf16_f32 v32, v44, v45
	v_cvt_pk_bf16_f32 v33, v46, v47
	v_cvt_pk_bf16_f32 v34, v40, v41
	v_cvt_pk_bf16_f32 v35, v42, v43
	v_cvt_pk_bf16_f32 v36, v36, v37
	v_cvt_pk_bf16_f32 v37, v38, v39
	v_cvt_pk_bf16_f32 v38, v52, v53
	v_cvt_pk_bf16_f32 v39, v54, v55
	global_store_dwordx4 v[50:51], v[32:35], off
	global_store_dwordx4 v[48:49], v[36:39], off offset:256
	s_nop 1
	s_nop 0
	v_fmamk_f32 v32, v235, 0x3a800000, v174
	v_mul_f32_e32 v33, 0x4f800000, v32
	v_cmp_gt_f32_e32 vcc, s75, v32
	s_nop 1
	v_cndmask_b32_e32 v34, v32, v33, vcc
	v_sqrt_f32_e32 v35, v34
	v_lshl_add_u64 v[32:33], v[162:163], 0, s[26:27]
	v_add_u32_e32 v36, -1, v35
	v_add_u32_e32 v37, 1, v35
	v_fma_f32 v38, -v36, v35, v34
	v_fma_f32 v39, -v37, v35, v34
	v_cmp_ge_f32_e64 s[4:5], 0, v38
	s_nop 1
	v_cndmask_b32_e64 v35, v35, v36, s[4:5]
	v_cmp_lt_f32_e64 s[4:5], 0, v39
	s_nop 1
	v_cndmask_b32_e64 v35, v35, v37, s[4:5]
	v_mul_f32_e32 v36, 0x37800000, v35
	v_cndmask_b32_e32 v35, v35, v36, vcc
	v_cmp_class_f32_e32 vcc, v34, v175
	s_nop 1
	v_cndmask_b32_e32 v36, v35, v34, vcc
	v_div_scale_f32 v37, s[4:5], v36, v36, 1.0
	v_rcp_f32_e32 v38, v37
	v_add_co_u32_e32 v34, vcc, s78, v162
	v_fma_f32 v40, -v37, v38, 1.0
	s_nop 0
	v_addc_co_u32_e32 v35, vcc, 0, v163, vcc
	v_div_scale_f32 v39, vcc, 1.0, v36, 1.0
	v_fmac_f32_e32 v38, v40, v38
	v_mul_f32_e32 v40, v39, v38
	v_fma_f32 v41, -v37, v40, v39
	v_fmac_f32_e32 v40, v41, v38
	v_fma_f32 v37, -v37, v40, v39
	v_div_fmas_f32 v37, v37, v38, v40
	v_div_fixup_f32 v36, v37, v36, 1.0
	v_pk_fma_f32 v[30:31], v[30:31], v[36:37], v[102:103] op_sel_hi:[1,0,1]
	v_pk_fma_f32 v[28:29], v[28:29], v[36:37], v[100:101] op_sel_hi:[1,0,1]
	v_pk_fma_f32 v[26:27], v[26:27], v[36:37], v[98:99] op_sel_hi:[1,0,1]
	v_pk_fma_f32 v[24:25], v[24:25], v[36:37], v[96:97] op_sel_hi:[1,0,1]
	v_pk_fma_f32 v[22:23], v[22:23], v[36:37], v[94:95] op_sel_hi:[1,0,1]
	v_pk_fma_f32 v[20:21], v[20:21], v[36:37], v[92:93] op_sel_hi:[1,0,1]
	v_pk_fma_f32 v[18:19], v[18:19], v[36:37], v[90:91] op_sel_hi:[1,0,1]
	v_pk_fma_f32 v[16:17], v[16:17], v[36:37], v[88:89] op_sel_hi:[1,0,1]
	v_max_f32_e32 v28, 0, v28
	v_max_f32_e32 v24, 0, v24
	v_max_f32_e32 v29, 0, v29
	v_max_f32_e32 v25, 0, v25
	v_max_f32_e32 v30, 0, v30
	v_max_f32_e32 v26, 0, v26
	v_max_f32_e32 v31, 0, v31
	v_max_f32_e32 v27, 0, v27
	v_max_f32_e32 v20, 0, v20
	v_max_f32_e32 v16, 0, v16
	v_max_f32_e32 v21, 0, v21
	v_max_f32_e32 v17, 0, v17
	v_max_f32_e32 v22, 0, v22
	v_max_f32_e32 v18, 0, v18
	v_max_f32_e32 v23, 0, v23
	v_max_f32_e32 v19, 0, v19
	v_pk_mul_f32 v[28:29], v[28:29], v[28:29]
	v_pk_mul_f32 v[24:25], v[24:25], v[24:25]
	v_pk_mul_f32 v[30:31], v[30:31], v[30:31]
	v_pk_mul_f32 v[26:27], v[26:27], v[26:27]
	v_pk_mul_f32 v[20:21], v[20:21], v[20:21]
	v_pk_mul_f32 v[36:37], v[16:17], v[16:17]
	v_pk_mul_f32 v[22:23], v[22:23], v[22:23]
	v_pk_mul_f32 v[38:39], v[18:19], v[18:19]
	v_cvt_pk_bf16_f32 v16, v28, v29
	v_cvt_pk_bf16_f32 v17, v30, v31
	v_cvt_pk_bf16_f32 v18, v24, v25
	v_cvt_pk_bf16_f32 v19, v26, v27
	v_cvt_pk_bf16_f32 v20, v20, v21
	v_cvt_pk_bf16_f32 v21, v22, v23
	v_cvt_pk_bf16_f32 v22, v36, v37
	v_cvt_pk_bf16_f32 v23, v38, v39
	global_store_dwordx4 v[34:35], v[16:19], off
	global_store_dwordx4 v[32:33], v[20:23], off offset:256
	s_nop 1
	s_nop 0
	v_fmamk_f32 v16, v236, 0x3a800000, v174
	v_mul_f32_e32 v17, 0x4f800000, v16
	v_cmp_gt_f32_e32 vcc, s75, v16
	s_nop 1
	v_cndmask_b32_e32 v18, v16, v17, vcc
	v_sqrt_f32_e32 v19, v18
	v_lshl_add_u64 v[16:17], v[162:163], 0, s[28:29]
	v_add_u32_e32 v20, -1, v19
	v_add_u32_e32 v21, 1, v19
	v_fma_f32 v22, -v20, v19, v18
	v_fma_f32 v23, -v21, v19, v18
	v_cmp_ge_f32_e64 s[4:5], 0, v22
	s_nop 1
	v_cndmask_b32_e64 v19, v19, v20, s[4:5]
	v_cmp_lt_f32_e64 s[4:5], 0, v23
	s_nop 1
	v_cndmask_b32_e64 v19, v19, v21, s[4:5]
	v_mul_f32_e32 v20, 0x37800000, v19
	v_cndmask_b32_e32 v19, v19, v20, vcc
	v_cmp_class_f32_e32 vcc, v18, v175
	s_nop 1
	v_cndmask_b32_e32 v20, v19, v18, vcc
	v_div_scale_f32 v21, s[4:5], v20, v20, 1.0
	v_rcp_f32_e32 v22, v21
	v_add_co_u32_e32 v18, vcc, s79, v162
	v_fma_f32 v24, -v21, v22, 1.0
	s_nop 0
	v_addc_co_u32_e32 v19, vcc, 0, v163, vcc
	v_div_scale_f32 v23, vcc, 1.0, v20, 1.0
	v_fmac_f32_e32 v22, v24, v22
	v_mul_f32_e32 v24, v23, v22
	v_fma_f32 v25, -v21, v24, v23
	v_fmac_f32_e32 v24, v25, v22
	v_fma_f32 v21, -v21, v24, v23
	v_div_fmas_f32 v21, v21, v22, v24
	v_div_fixup_f32 v20, v21, v20, 1.0
	v_pk_fma_f32 v[14:15], v[14:15], v[20:21], v[102:103] op_sel_hi:[1,0,1]
	v_pk_fma_f32 v[12:13], v[12:13], v[20:21], v[100:101] op_sel_hi:[1,0,1]
	v_pk_fma_f32 v[10:11], v[10:11], v[20:21], v[98:99] op_sel_hi:[1,0,1]
	v_pk_fma_f32 v[8:9], v[8:9], v[20:21], v[96:97] op_sel_hi:[1,0,1]
	v_pk_fma_f32 v[6:7], v[6:7], v[20:21], v[94:95] op_sel_hi:[1,0,1]
	v_pk_fma_f32 v[4:5], v[4:5], v[20:21], v[92:93] op_sel_hi:[1,0,1]
	v_pk_fma_f32 v[2:3], v[2:3], v[20:21], v[90:91] op_sel_hi:[1,0,1]
	v_pk_fma_f32 v[0:1], v[0:1], v[20:21], v[88:89] op_sel_hi:[1,0,1]
	v_max_f32_e32 v12, 0, v12
	v_max_f32_e32 v8, 0, v8
	v_max_f32_e32 v13, 0, v13
	v_max_f32_e32 v9, 0, v9
	v_max_f32_e32 v14, 0, v14
	v_max_f32_e32 v10, 0, v10
	v_max_f32_e32 v15, 0, v15
	v_max_f32_e32 v11, 0, v11
	v_max_f32_e32 v4, 0, v4
	v_max_f32_e32 v0, 0, v0
	v_max_f32_e32 v5, 0, v5
	v_max_f32_e32 v1, 0, v1
	v_max_f32_e32 v6, 0, v6
	v_max_f32_e32 v2, 0, v2
	v_max_f32_e32 v7, 0, v7
	v_max_f32_e32 v3, 0, v3
	v_pk_mul_f32 v[12:13], v[12:13], v[12:13]
	v_pk_mul_f32 v[8:9], v[8:9], v[8:9]
	v_pk_mul_f32 v[14:15], v[14:15], v[14:15]
	v_pk_mul_f32 v[10:11], v[10:11], v[10:11]
	s_andn2_b64 vcc, exec, s[0:1]
	v_pk_mul_f32 v[4:5], v[4:5], v[4:5]
	v_pk_mul_f32 v[20:21], v[0:1], v[0:1]
	v_pk_mul_f32 v[6:7], v[6:7], v[6:7]
	v_pk_mul_f32 v[22:23], v[2:3], v[2:3]
	v_cvt_pk_bf16_f32 v0, v12, v13
	v_cvt_pk_bf16_f32 v1, v14, v15
	v_cvt_pk_bf16_f32 v2, v8, v9
	v_cvt_pk_bf16_f32 v3, v10, v11
	s_mov_b64 s[0:1], -1
	v_cvt_pk_bf16_f32 v4, v4, v5
	v_cvt_pk_bf16_f32 v5, v6, v7
	v_cvt_pk_bf16_f32 v6, v20, v21
	v_cvt_pk_bf16_f32 v7, v22, v23
	global_store_dwordx4 v[18:19], v[0:3], off
	global_store_dwordx4 v[16:17], v[4:7], off offset:256
	s_cbranch_vccnz .LBB0_745
	s_andn2_b64 vcc, exec, s[8:9]
	s_cbranch_vccnz .LBB0_744
	s_barrier
	s_branch .LBB0_744
